# flat barrier release without the unused per-XCD relay atomic in the leader path; otherwise as v76 (LDS-image U/w_up/w_down layouts)
# baseline (speedup 1.0000x reference)
.LBB0_20:
	s_or_b64 exec, exec, s[40:41]
	v_readlane_b32 s38, v250, 48
	v_readlane_b32 s39, v250, 49
	s_waitcnt vmcnt(0)
	buffer_inv sc1
	s_nop 2
	s_nop 0
	s_waitcnt vmcnt(0)

.LBB0_140:
	s_or_b64 exec, exec, s[4:5]
	v_readlane_b32 s4, v253, 25
	v_readlane_b32 s5, v253, 26
	s_waitcnt vmcnt(0)
	buffer_inv sc1
	s_nop 2
	s_nop 0
	s_waitcnt vmcnt(0)

.LBB0_271:
	s_or_b64 exec, exec, s[14:15]
	v_readlane_b32 s14, v253, 25
	v_readlane_b32 s15, v253, 26
	s_waitcnt vmcnt(0)
	buffer_inv sc1
	s_nop 2
	s_nop 0
	s_waitcnt vmcnt(0)

.LBB0_1748:
	s_or_b64 exec, exec, s[8:9]
	v_readlane_b32 s8, v253, 25
	v_readlane_b32 s9, v253, 26
	s_waitcnt vmcnt(0)
	buffer_inv sc1
	s_nop 2
	s_nop 0
	s_waitcnt vmcnt(0)
